# P10 modulate loop: row chunks and all scale/shift loads issued up front, gain vector hoisted, stores without per-chunk drains
# baseline (speedup 1.0000x reference)
.LBB0_618:
	v_mov_b32_e32 v0, v228
	v_readlane_b32 s0, v253, 38
	v_ashrrev_i32_e32 v1, 6, v0
	s_nop 0
	v_add_u32_e32 v42, s0, v1
	s_mov_b32 s0, 0x8800
	v_cmp_gt_i32_e32 vcc, s0, v42
	s_and_saveexec_b64 s[0:1], vcc
	s_cbranch_execz .LBB0_625
	v_and_b32_e32 v1, 64, v229
	v_add_u32_e32 v1, 64, v1
	v_xor_b32_e32 v2, 32, v229
	v_cmp_lt_i32_e32 vcc, v2, v1
	v_readlane_b32 s4, v253, 18
	v_readlane_b32 s5, v253, 19
	v_cndmask_b32_e32 v2, v229, v2, vcc
	v_lshlrev_b32_e32 v43, 2, v2
	v_xor_b32_e32 v2, 16, v229
	v_cmp_lt_i32_e32 vcc, v2, v1
	v_readlane_b32 s12, v253, 26
	v_readlane_b32 s13, v253, 27
	v_cndmask_b32_e32 v2, v229, v2, vcc
	v_lshlrev_b32_e32 v44, 2, v2
	v_xor_b32_e32 v2, 8, v229
	v_cmp_lt_i32_e32 vcc, v2, v1
	v_readlane_b32 s16, v253, 30
	v_readlane_b32 s17, v253, 31
	v_cndmask_b32_e32 v2, v229, v2, vcc
	v_lshlrev_b32_e32 v45, 2, v2
	v_xor_b32_e32 v2, 4, v229
	v_cmp_lt_i32_e32 vcc, v2, v1
	v_readlane_b32 s4, v253, 36
	s_mov_b64 s[12:13], s[16:17]
	v_cndmask_b32_e32 v2, v229, v2, vcc
	v_lshlrev_b32_e32 v46, 2, v2
	v_xor_b32_e32 v2, 2, v229
	v_cmp_lt_i32_e32 vcc, v2, v1
	v_lshlrev_b32_e32 v0, 2, v0
	v_readlane_b32 s5, v253, 37
	v_cndmask_b32_e32 v2, v229, v2, vcc
	v_lshlrev_b32_e32 v47, 2, v2
	v_xor_b32_e32 v2, 1, v229
	s_add_u32 s2, s12, 0x1000
	v_and_b32_e32 v0, 0xfc, v0
	s_load_dword s4, s[4:5], 0x0
	v_cmp_lt_i32_e32 vcc, v2, v1
	s_addc_u32 s3, s13, 0
	v_mov_b32_e32 v17, 0
	v_cndmask_b32_e32 v1, v229, v2, vcc
	v_lshlrev_b32_e32 v16, 2, v0
	v_or_b32_e32 v2, 0x100, v0
	v_lshl_add_u64 v[18:19], s[2:3], 0, v[16:17]
	v_or_b32_e32 v4, 0x200, v0
	v_lshlrev_b32_e32 v16, 2, v2
	v_or_b32_e32 v6, 0x300, v0
	v_lshl_add_u64 v[20:21], s[2:3], 0, v[16:17]
	v_lshlrev_b32_e32 v16, 2, v4
	v_readlane_b32 s6, v253, 20
	v_lshl_add_u64 v[22:23], s[2:3], 0, v[16:17]
	v_lshlrev_b32_e32 v16, 2, v6
	v_lshlrev_b32_e32 v48, 2, v1
	s_waitcnt lgkmcnt(0)
	s_lshl_b32 s6, s4, 3
	v_lshl_add_u64 v[24:25], s[2:3], 0, v[16:17]
	s_mov_b64 s[2:3], 0
	v_lshlrev_b32_e32 v26, 2, v0
	v_mov_b32_e32 v27, v17
	v_mov_b32_e32 v49, 0x358637bd
	v_mov_b64_e32 v[28:29], s[86:87]
	v_lshlrev_b32_e32 v30, 1, v0
	v_mov_b32_e32 v31, v17
	v_lshlrev_b32_e32 v32, 2, v2
	v_mov_b32_e32 v33, v17
	v_lshlrev_b32_e32 v34, 2, v4
	v_mov_b32_e32 v35, v17
	v_lshlrev_b32_e32 v36, 2, v6
	v_mov_b32_e32 v37, v17
	v_readlane_b32 s7, v253, 21
	v_readlane_b32 s8, v253, 22
	v_readlane_b32 s9, v253, 23
	v_readlane_b32 s10, v253, 24
	v_readlane_b32 s11, v253, 25
	v_readlane_b32 s14, v253, 28
	v_readlane_b32 s15, v253, 29
	v_readlane_b32 s18, v253, 32
	v_readlane_b32 s19, v253, 33
	global_load_dwordx4 v[104:107], v[18:19], off
	global_load_dwordx4 v[108:111], v[20:21], off
	global_load_dwordx4 v[112:115], v[22:23], off
	global_load_dwordx4 v[116:119], v[24:25], off
	s_branch .LBB0_621
.LBB0_620:
	s_or_b64 exec, exec, s[4:5]
	v_lshlrev_b64 v[0:1], v4, v[0:1]
	v_lshl_add_u64 v[0:1], v[6:7], 0, v[0:1]
	v_lshlrev_b64 v[2:3], 12, v[2:3]
	v_lshl_add_u64 v[0:1], v[0:1], 0, v[2:3]
	v_lshl_add_u64 v[64:65], v[0:1], 0, v[26:27]
	global_load_dwordx4 v[12:15], v[64:65], off nt
	global_load_dwordx4 v[8:11], v[64:65], off offset:1024 nt
	global_load_dwordx4 v[4:7], v[64:65], off offset:2048 nt
	global_load_dwordx4 v[0:3], v[64:65], off offset:3072 nt
	v_ashrrev_i32_e32 v40, 13, v40
	v_lshl_add_u64 v[38:39], s[28:29], 0, v[38:39]
	s_mov_b64 s[4:5], 0x1000
	v_lshl_add_u64 v[66:67], v[38:39], 0, s[4:5]
	v_lshl_add_u64 v[38:39], v[38:39], 0, v[26:27]
	v_lshl_add_u64 v[68:69], v[66:67], 0, v[26:27]
	global_load_dwordx4 v[72:75], v[38:39], off
	global_load_dwordx4 v[88:91], v[68:69], off
	v_lshl_add_u64 v[68:69], v[66:67], 0, v[32:33]
	global_load_dwordx4 v[76:79], v[38:39], off offset:1024
	global_load_dwordx4 v[92:95], v[68:69], off
	v_lshl_add_u64 v[68:69], v[66:67], 0, v[34:35]
	global_load_dwordx4 v[80:83], v[38:39], off offset:2048
	global_load_dwordx4 v[96:99], v[68:69], off
	v_lshl_add_u64 v[68:69], v[66:67], 0, v[36:37]
	global_load_dwordx4 v[84:87], v[38:39], off offset:3072
	global_load_dwordx4 v[100:103], v[68:69], off
	s_mov_b32 s4, 0x800000
	s_waitcnt vmcnt(11)
	v_mov_b32_e32 v120, v13
	s_waitcnt vmcnt(10)
	v_mov_b32_e32 v121, v9
	v_mov_b32_e32 v122, v12
	v_mov_b32_e32 v123, v8
	v_pk_mul_f32 v[120:121], v[120:121], v[120:121]
	s_nop 0
	v_pk_fma_f32 v[122:123], v[122:123], v[122:123], v[120:121]
	v_mov_b32_e32 v120, v14
	v_mov_b32_e32 v121, v10
	v_pk_fma_f32 v[122:123], v[120:121], v[120:121], v[122:123]
	v_mov_b32_e32 v120, v15
	v_mov_b32_e32 v121, v11
	v_pk_fma_f32 v[50:51], v[120:121], v[120:121], v[122:123]
	s_nop 0
	v_add_f32_e32 v16, v50, v51
	s_waitcnt vmcnt(9)
	v_mov_b32_e32 v54, v5
	s_waitcnt vmcnt(8)
	v_mov_b32_e32 v55, v1
	v_mov_b32_e32 v52, v4
	v_mov_b32_e32 v53, v0
	v_pk_mul_f32 v[54:55], v[54:55], v[54:55]
	s_nop 0
	v_pk_fma_f32 v[52:53], v[52:53], v[52:53], v[54:55]
	v_mov_b32_e32 v54, v6
	v_mov_b32_e32 v55, v2
	v_pk_fma_f32 v[52:53], v[54:55], v[54:55], v[52:53]
	v_mov_b32_e32 v54, v7
	v_mov_b32_e32 v55, v3
	v_pk_fma_f32 v[52:53], v[54:55], v[54:55], v[52:53]
	s_nop 0
	v_add_f32_e32 v16, v16, v52
	v_add_f32_e32 v16, v16, v53
	ds_bpermute_b32 v50, v43, v16
	s_waitcnt lgkmcnt(0)
	v_add_f32_e32 v16, v16, v50
	ds_bpermute_b32 v50, v44, v16
	s_waitcnt lgkmcnt(0)
	v_add_f32_e32 v16, v16, v50
	ds_bpermute_b32 v50, v45, v16
	s_waitcnt lgkmcnt(0)
	v_add_f32_e32 v16, v16, v50
	ds_bpermute_b32 v50, v46, v16
	s_waitcnt lgkmcnt(0)
	v_add_f32_e32 v16, v16, v50
	ds_bpermute_b32 v50, v47, v16
	s_waitcnt lgkmcnt(0)
	v_add_f32_e32 v16, v16, v50
	ds_bpermute_b32 v50, v48, v16
	s_waitcnt lgkmcnt(0)
	v_add_f32_e32 v16, v16, v50
	v_fmamk_f32 v16, v16, 0x3a800000, v49
	v_cmp_gt_f32_e32 vcc, s4, v16
	v_mul_f32_e32 v50, 0x4b800000, v16
	s_mov_b32 s4, 0x2200000
	v_cndmask_b32_e32 v16, v16, v50, vcc
	v_rsq_f32_e32 v16, v16
	s_nop 0
	v_mul_f32_e32 v50, 0x45800000, v16
	v_cndmask_b32_e32 v16, v16, v50, vcc
	v_add_u32_e32 v50, v40, v41
	v_mad_i64_i32 v[40:41], s[4:5], v50, s4, v[28:29]
	v_mul_i32_i24_e32 v50, 0x4400, v50
	v_sub_u32_e32 v50, v42, v50
	v_ashrrev_i32_e32 v51, 31, v50
	v_lshlrev_b64 v[50:51], 11, v[50:51]
	v_lshl_add_u64 v[62:63], v[40:41], 0, v[50:51]
	s_waitcnt vmcnt(0)
	v_pk_mul_f32 v[12:13], v[12:13], v[16:17] op_sel_hi:[1,0]
	v_pk_mul_f32 v[14:15], v[14:15], v[16:17] op_sel_hi:[1,0]
	v_pk_mul_f32 v[8:9], v[8:9], v[16:17] op_sel_hi:[1,0]
	v_pk_mul_f32 v[10:11], v[10:11], v[16:17] op_sel_hi:[1,0]
	v_pk_mul_f32 v[4:5], v[4:5], v[16:17] op_sel_hi:[1,0]
	v_pk_mul_f32 v[6:7], v[6:7], v[16:17] op_sel_hi:[1,0]
	v_pk_mul_f32 v[0:1], v[0:1], v[16:17] op_sel_hi:[1,0]
	v_pk_mul_f32 v[2:3], v[2:3], v[16:17] op_sel_hi:[1,0]
	v_lshl_add_u64 v[126:127], v[62:63], 0, v[30:31]
	v_add_u32_e32 v42, s6, v42
	v_pk_mul_f32 v[12:13], v[104:105], v[12:13]
	v_pk_mul_f32 v[14:15], v[106:107], v[14:15]
	v_pk_add_f32 v[50:51], v[88:89], 1.0 op_sel_hi:[1,0]
	v_pk_add_f32 v[52:53], v[90:91], 1.0 op_sel_hi:[1,0]
	v_pk_mul_f32 v[8:9], v[8:9], v[108:109]
	v_pk_fma_f32 v[12:13], v[50:51], v[12:13], v[72:73]
	v_pk_fma_f32 v[14:15], v[52:53], v[14:15], v[74:75]
	v_pk_mul_f32 v[10:11], v[10:11], v[110:111]
	v_pk_add_f32 v[50:51], v[92:93], 1.0 op_sel_hi:[1,0]
	v_cvt_pk_bf16_f32 v120, v12, v13
	v_cvt_pk_bf16_f32 v121, v14, v15
	global_store_dwordx2 v[126:127], v[120:121], off
	v_pk_add_f32 v[52:53], v[94:95], 1.0 op_sel_hi:[1,0]
	v_pk_fma_f32 v[8:9], v[8:9], v[50:51], v[76:77]
	v_pk_mul_f32 v[4:5], v[4:5], v[112:113]
	v_pk_fma_f32 v[10:11], v[10:11], v[52:53], v[78:79]
	v_pk_mul_f32 v[6:7], v[6:7], v[114:115]
	v_pk_add_f32 v[50:51], v[96:97], 1.0 op_sel_hi:[1,0]
	v_cvt_pk_bf16_f32 v122, v8, v9
	v_cvt_pk_bf16_f32 v123, v10, v11
	global_store_dwordx2 v[126:127], v[122:123], off offset:512
	v_pk_add_f32 v[52:53], v[98:99], 1.0 op_sel_hi:[1,0]
	v_pk_fma_f32 v[4:5], v[4:5], v[50:51], v[80:81]
	v_pk_mul_f32 v[0:1], v[0:1], v[116:117]
	v_pk_fma_f32 v[6:7], v[6:7], v[52:53], v[82:83]
	v_pk_mul_f32 v[2:3], v[2:3], v[118:119]
	v_pk_add_f32 v[50:51], v[100:101], 1.0 op_sel_hi:[1,0]
	v_cvt_pk_bf16_f32 v124, v4, v5
	v_cvt_pk_bf16_f32 v125, v6, v7
	global_store_dwordx2 v[126:127], v[124:125], off offset:1024
	v_pk_add_f32 v[52:53], v[102:103], 1.0 op_sel_hi:[1,0]
	v_pk_fma_f32 v[0:1], v[0:1], v[50:51], v[84:85]
	s_mov_b32 s4, 0x87ff
	v_cmp_lt_i32_e32 vcc, s4, v42
	v_pk_fma_f32 v[2:3], v[2:3], v[52:53], v[86:87]
	s_or_b64 s[2:3], vcc, s[2:3]
	v_cvt_pk_bf16_f32 v0, v0, v1
	s_nop 0
	v_cvt_pk_bf16_f32 v1, v2, v3
	global_store_dwordx2 v[126:127], v[0:1], off offset:1536
	s_andn2_b64 exec, exec, s[2:3]
	s_cbranch_execz .LBB0_625
